# v44 plus the GEMM K-loop header aligned to a 64-byte boundary
# baseline (speedup 1.0000x reference)
; __device__ __forceinline__ void gemm_phase(PG8_LAS unsigned char* lds, const Gemm g, const StaticOrder& S, const Epi& E, const int tid) {
;     ...
; #pragma unroll
;         for (int a = 0; a < 2; ++a)
; #pragma unroll
;             for (int b = 0; b < 2; ++b)
; #pragma unroll
;                 for (int m = 0; m < 4; ++m)
; #pragma unroll
;                     for (int n = 0; n < 2; ++n) acc[a][b][m][n] = (f32x4){0.f, 0.f, 0.f, 0.f};
;         cur = nxt; cA = nA; cB = nB; ++ui;
.LBB0_87:
	s_add_u32 s10, s10, 0x80
	s_addc_u32 s11, s11, 0
	s_add_u32 s47, s44, 0x100
	v_mov_b32_e32 v2, 0
	s_addc_u32 s48, s45, 0
	s_mov_b32 s44, 0
	v_mov_b32_e32 v3, v2
	v_mov_b32_e32 v4, v2
	v_mov_b32_e32 v5, v2
	v_mov_b32_e32 v6, v2
	v_mov_b32_e32 v7, v2
	v_mov_b32_e32 v8, v2
	v_mov_b32_e32 v9, v2
	v_mov_b32_e32 v18, v2
	v_mov_b32_e32 v19, v2
	v_mov_b32_e32 v20, v2
	v_mov_b32_e32 v21, v2
	v_mov_b32_e32 v22, v2
	v_mov_b32_e32 v23, v2
	v_mov_b32_e32 v24, v2
	v_mov_b32_e32 v25, v2
	v_mov_b32_e32 v34, v2
	v_mov_b32_e32 v35, v2
	v_mov_b32_e32 v36, v2
	v_mov_b32_e32 v37, v2
	v_mov_b32_e32 v38, v2
	v_mov_b32_e32 v39, v2
	v_mov_b32_e32 v40, v2
	v_mov_b32_e32 v41, v2
	v_mov_b32_e32 v50, v2
	v_mov_b32_e32 v51, v2
	v_mov_b32_e32 v52, v2
	v_mov_b32_e32 v53, v2
	v_mov_b32_e32 v54, v2
	v_mov_b32_e32 v55, v2
	v_mov_b32_e32 v56, v2
	v_mov_b32_e32 v57, v2
	v_mov_b32_e32 v10, v2
	v_mov_b32_e32 v11, v2
	v_mov_b32_e32 v12, v2
	v_mov_b32_e32 v13, v2
	v_mov_b32_e32 v14, v2
	v_mov_b32_e32 v15, v2
	v_mov_b32_e32 v16, v2
	v_mov_b32_e32 v17, v2
	v_mov_b32_e32 v26, v2
	v_mov_b32_e32 v27, v2
	v_mov_b32_e32 v28, v2
	v_mov_b32_e32 v29, v2
	v_mov_b32_e32 v30, v2
	v_mov_b32_e32 v31, v2
	v_mov_b32_e32 v32, v2
	v_mov_b32_e32 v33, v2
	v_mov_b32_e32 v42, v2
	v_mov_b32_e32 v43, v2
	v_mov_b32_e32 v44, v2
	v_mov_b32_e32 v45, v2
	v_mov_b32_e32 v46, v2
	v_mov_b32_e32 v47, v2
	v_mov_b32_e32 v48, v2
	v_mov_b32_e32 v49, v2
	v_mov_b32_e32 v58, v2
	v_mov_b32_e32 v59, v2
	v_mov_b32_e32 v60, v2
	v_mov_b32_e32 v61, v2
	v_mov_b32_e32 v62, v2
	v_mov_b32_e32 v63, v2
	v_mov_b32_e32 v64, v2
	v_mov_b32_e32 v65, v2
	v_mov_b32_e32 v66, v2
	v_mov_b32_e32 v67, v2
	v_mov_b32_e32 v68, v2
	v_mov_b32_e32 v69, v2
	v_mov_b32_e32 v70, v2
	v_mov_b32_e32 v71, v2
	v_mov_b32_e32 v72, v2
	v_mov_b32_e32 v73, v2
	v_mov_b32_e32 v82, v2
	v_mov_b32_e32 v83, v2
	v_mov_b32_e32 v84, v2
	v_mov_b32_e32 v85, v2
	v_mov_b32_e32 v86, v2
	v_mov_b32_e32 v87, v2
	v_mov_b32_e32 v88, v2
	v_mov_b32_e32 v89, v2
	v_mov_b32_e32 v98, v2
	v_mov_b32_e32 v99, v2
	v_mov_b32_e32 v100, v2
	v_mov_b32_e32 v101, v2
	v_mov_b32_e32 v102, v2
	v_mov_b32_e32 v103, v2
	v_mov_b32_e32 v104, v2
	v_mov_b32_e32 v105, v2
	v_mov_b32_e32 v120, v2
	v_mov_b32_e32 v121, v2
	v_mov_b32_e32 v122, v2
	v_mov_b32_e32 v123, v2
	v_mov_b32_e32 v124, v2
	v_mov_b32_e32 v125, v2
	v_mov_b32_e32 v126, v2
	v_mov_b32_e32 v127, v2
	v_mov_b32_e32 v74, v2
	v_mov_b32_e32 v75, v2
	v_mov_b32_e32 v76, v2
	v_mov_b32_e32 v77, v2
	v_mov_b32_e32 v78, v2
	v_mov_b32_e32 v79, v2
	v_mov_b32_e32 v80, v2
	v_mov_b32_e32 v81, v2
	v_mov_b32_e32 v90, v2
	v_mov_b32_e32 v91, v2
	v_mov_b32_e32 v92, v2
	v_mov_b32_e32 v93, v2
	v_mov_b32_e32 v94, v2
	v_mov_b32_e32 v95, v2
	v_mov_b32_e32 v96, v2
	v_mov_b32_e32 v97, v2
	v_mov_b32_e32 v106, v2
	v_mov_b32_e32 v107, v2
	v_mov_b32_e32 v108, v2
	v_mov_b32_e32 v109, v2
	v_mov_b32_e32 v116, v2
	v_mov_b32_e32 v117, v2
	v_mov_b32_e32 v118, v2
	v_mov_b32_e32 v119, v2
	v_mov_b32_e32 v128, v2
	v_mov_b32_e32 v129, v2
	v_mov_b32_e32 v130, v2
	v_mov_b32_e32 v131, v2
	v_mov_b32_e32 v132, v2
	v_mov_b32_e32 v133, v2
	v_mov_b32_e32 v134, v2
	v_mov_b32_e32 v135, v2
	.p2align 6
